# phase_ada k-loop: weight-row loads issued 13 groups ahead behind counted vmcnt, plain f32 FMA chain, LDS rows double buffered
# speedup vs baseline: 1.0186x; 1.0004x over previous
.LBB0_20:
	s_mul_hi_i32 s0, s7, 0x38e38e39
	s_lshr_b32 s1, s0, 31
	s_ashr_i32 s8, s0, 5
	s_add_i32 s8, s8, s1
	s_mul_i32 s0, s8, 0x90
	s_sub_i32 s0, s7, s0
	s_lshl_b32 s1, s0, 6
	v_mov_b32_e32 v2, v179
	s_and_b32 s9, s0, 7
	s_and_b32 s0, s7, 7
	s_and_b32 s1, s1, 0xfffffe00
	s_mul_i32 s14, s8, 0x2400000
	s_mul_i32 s0, s0, 0x480000
	v_add_u32_e32 v2, s1, v2
	s_mul_hi_i32 s1, s8, 0x2400000
	s_add_u32 s0, s14, s0
	v_readlane_b32 s36, v249, 0
	s_addc_u32 s1, s1, 0
	v_readlane_b32 s40, v249, 4
	v_readlane_b32 s41, v249, 5
	s_add_u32 s0, s40, s0
	v_ashrrev_i32_e32 v3, 31, v2
	s_addc_u32 s1, s41, s1
	v_lshl_add_u64 v[12:13], v[2:3], 2, s[0:1]
	s_lshl_b32 s0, s9, 9
	v_mov_b32_e32 v4, 0
	s_add_i32 s14, s0, 0
	s_mov_b64 s[0:1], 0
	v_mov_b32_e32 v5, v4
	v_mov_b32_e32 v10, v4
	v_mov_b32_e32 v11, v4
	v_mov_b32_e32 v8, v4
	v_mov_b32_e32 v9, v4
	v_mov_b32_e32 v6, v4
	v_mov_b32_e32 v7, v4
	v_readlane_b32 s37, v249, 1
	v_readlane_b32 s38, v249, 2
	v_readlane_b32 s39, v249, 3
	v_readlane_b32 s42, v249, 6
	v_readlane_b32 s43, v249, 7
	v_mov_b32_e32 v202, s14
	v_mov_b32_e32 v194, v12
	v_mov_b32_e32 v195, v13
	v_add_co_u32_e32 v196, vcc, s4, v12
	s_nop 1
	v_addc_co_u32_e32 v197, vcc, 0, v13, vcc
	v_add_co_u32_e32 v198, vcc, s5, v12
	s_nop 1
	v_addc_co_u32_e32 v199, vcc, 0, v13, vcc
	v_add_co_u32_e32 v200, vcc, s6, v12
	s_nop 1
	v_addc_co_u32_e32 v201, vcc, 0, v13, vcc
	s_mov_b32 s0, 0x24000
	s_mov_b32 s1, 0
	global_load_dword v64, v[194:195], off
	v_lshl_add_u64 v[194:195], v[194:195], 0, s[0:1]
	global_load_dword v65, v[196:197], off
	v_lshl_add_u64 v[196:197], v[196:197], 0, s[0:1]
	global_load_dword v66, v[198:199], off
	v_lshl_add_u64 v[198:199], v[198:199], 0, s[0:1]
	global_load_dword v67, v[200:201], off
	v_lshl_add_u64 v[200:201], v[200:201], 0, s[0:1]
	global_load_dword v68, v[194:195], off
	v_lshl_add_u64 v[194:195], v[194:195], 0, s[0:1]
	global_load_dword v69, v[196:197], off
	v_lshl_add_u64 v[196:197], v[196:197], 0, s[0:1]
	global_load_dword v70, v[198:199], off
	v_lshl_add_u64 v[198:199], v[198:199], 0, s[0:1]
	global_load_dword v71, v[200:201], off
	v_lshl_add_u64 v[200:201], v[200:201], 0, s[0:1]
	global_load_dword v72, v[194:195], off
	v_lshl_add_u64 v[194:195], v[194:195], 0, s[0:1]
	global_load_dword v73, v[196:197], off
	v_lshl_add_u64 v[196:197], v[196:197], 0, s[0:1]
	global_load_dword v74, v[198:199], off
	v_lshl_add_u64 v[198:199], v[198:199], 0, s[0:1]
	global_load_dword v75, v[200:201], off
	v_lshl_add_u64 v[200:201], v[200:201], 0, s[0:1]
	global_load_dword v76, v[194:195], off
	v_lshl_add_u64 v[194:195], v[194:195], 0, s[0:1]
	global_load_dword v77, v[196:197], off
	v_lshl_add_u64 v[196:197], v[196:197], 0, s[0:1]
	global_load_dword v78, v[198:199], off
	v_lshl_add_u64 v[198:199], v[198:199], 0, s[0:1]
	global_load_dword v79, v[200:201], off
	v_lshl_add_u64 v[200:201], v[200:201], 0, s[0:1]
	global_load_dword v80, v[194:195], off
	v_lshl_add_u64 v[194:195], v[194:195], 0, s[0:1]
	global_load_dword v81, v[196:197], off
	v_lshl_add_u64 v[196:197], v[196:197], 0, s[0:1]
	global_load_dword v82, v[198:199], off
	v_lshl_add_u64 v[198:199], v[198:199], 0, s[0:1]
	global_load_dword v83, v[200:201], off
	v_lshl_add_u64 v[200:201], v[200:201], 0, s[0:1]
	global_load_dword v84, v[194:195], off
	v_lshl_add_u64 v[194:195], v[194:195], 0, s[0:1]
	global_load_dword v85, v[196:197], off
	v_lshl_add_u64 v[196:197], v[196:197], 0, s[0:1]
	global_load_dword v86, v[198:199], off
	v_lshl_add_u64 v[198:199], v[198:199], 0, s[0:1]
	global_load_dword v87, v[200:201], off
	v_lshl_add_u64 v[200:201], v[200:201], 0, s[0:1]
	global_load_dword v88, v[194:195], off
	v_lshl_add_u64 v[194:195], v[194:195], 0, s[0:1]
	global_load_dword v89, v[196:197], off
	v_lshl_add_u64 v[196:197], v[196:197], 0, s[0:1]
	global_load_dword v90, v[198:199], off
	v_lshl_add_u64 v[198:199], v[198:199], 0, s[0:1]
	global_load_dword v91, v[200:201], off
	v_lshl_add_u64 v[200:201], v[200:201], 0, s[0:1]
	global_load_dword v92, v[194:195], off
	v_lshl_add_u64 v[194:195], v[194:195], 0, s[0:1]
	global_load_dword v93, v[196:197], off
	v_lshl_add_u64 v[196:197], v[196:197], 0, s[0:1]
	global_load_dword v94, v[198:199], off
	v_lshl_add_u64 v[198:199], v[198:199], 0, s[0:1]
	global_load_dword v95, v[200:201], off
	v_lshl_add_u64 v[200:201], v[200:201], 0, s[0:1]
	global_load_dword v96, v[194:195], off
	v_lshl_add_u64 v[194:195], v[194:195], 0, s[0:1]
	global_load_dword v97, v[196:197], off
	v_lshl_add_u64 v[196:197], v[196:197], 0, s[0:1]
	global_load_dword v98, v[198:199], off
	v_lshl_add_u64 v[198:199], v[198:199], 0, s[0:1]
	global_load_dword v99, v[200:201], off
	v_lshl_add_u64 v[200:201], v[200:201], 0, s[0:1]
	global_load_dword v100, v[194:195], off
	v_lshl_add_u64 v[194:195], v[194:195], 0, s[0:1]
	global_load_dword v101, v[196:197], off
	v_lshl_add_u64 v[196:197], v[196:197], 0, s[0:1]
	global_load_dword v102, v[198:199], off
	v_lshl_add_u64 v[198:199], v[198:199], 0, s[0:1]
	global_load_dword v103, v[200:201], off
	v_lshl_add_u64 v[200:201], v[200:201], 0, s[0:1]
	global_load_dword v104, v[194:195], off
	v_lshl_add_u64 v[194:195], v[194:195], 0, s[0:1]
	global_load_dword v105, v[196:197], off
	v_lshl_add_u64 v[196:197], v[196:197], 0, s[0:1]
	global_load_dword v106, v[198:199], off
	v_lshl_add_u64 v[198:199], v[198:199], 0, s[0:1]
	global_load_dword v107, v[200:201], off
	v_lshl_add_u64 v[200:201], v[200:201], 0, s[0:1]
	global_load_dword v108, v[194:195], off
	v_lshl_add_u64 v[194:195], v[194:195], 0, s[0:1]
	global_load_dword v109, v[196:197], off
	v_lshl_add_u64 v[196:197], v[196:197], 0, s[0:1]
	global_load_dword v110, v[198:199], off
	v_lshl_add_u64 v[198:199], v[198:199], 0, s[0:1]
	global_load_dword v111, v[200:201], off
	v_lshl_add_u64 v[200:201], v[200:201], 0, s[0:1]
	global_load_dword v112, v[194:195], off
	v_lshl_add_u64 v[194:195], v[194:195], 0, s[0:1]
	global_load_dword v113, v[196:197], off
	v_lshl_add_u64 v[196:197], v[196:197], 0, s[0:1]
	global_load_dword v114, v[198:199], off
	v_lshl_add_u64 v[198:199], v[198:199], 0, s[0:1]
	global_load_dword v115, v[200:201], off
	v_lshl_add_u64 v[200:201], v[200:201], 0, s[0:1]
	ds_read_b128 v[14:17], v202 offset:0
	ds_read_b128 v[18:21], v202 offset:4096
	ds_read_b128 v[22:25], v202 offset:8192
	ds_read_b128 v[26:29], v202 offset:12288
	ds_read_b128 v[30:33], v202 offset:16384
	ds_read_b128 v[34:37], v202 offset:20480
	ds_read_b128 v[38:41], v202 offset:24576
	ds_read_b128 v[42:45], v202 offset:28672
	ds_read_b128 v[204:207], v202 offset:16
	ds_read_b128 v[208:211], v202 offset:4112
	ds_read_b128 v[212:215], v202 offset:8208
	ds_read_b128 v[216:219], v202 offset:12304
	ds_read_b128 v[220:223], v202 offset:16400
	ds_read_b128 v[224:227], v202 offset:20496
	ds_read_b128 v[228:231], v202 offset:24592
	ds_read_b128 v[232:235], v202 offset:28688
	s_waitcnt vmcnt(48) lgkmcnt(8)
	v_fma_f32 v10, v64, v14, v10
	v_fma_f32 v11, v64, v18, v11
	v_fma_f32 v8, v64, v22, v8
	v_fma_f32 v9, v64, v26, v9
	v_fma_f32 v6, v64, v30, v6
	v_fma_f32 v7, v64, v34, v7
	v_fma_f32 v4, v64, v38, v4
	v_fma_f32 v5, v64, v42, v5
	v_fma_f32 v10, v65, v15, v10
	v_fma_f32 v11, v65, v19, v11
	v_fma_f32 v8, v65, v23, v8
	v_fma_f32 v9, v65, v27, v9
	v_fma_f32 v6, v65, v31, v6
	v_fma_f32 v7, v65, v35, v7
	v_fma_f32 v4, v65, v39, v4
	v_fma_f32 v5, v65, v43, v5
	v_fma_f32 v10, v66, v16, v10
	v_fma_f32 v11, v66, v20, v11
	v_fma_f32 v8, v66, v24, v8
	v_fma_f32 v9, v66, v28, v9
	v_fma_f32 v6, v66, v32, v6
	v_fma_f32 v7, v66, v36, v7
	v_fma_f32 v4, v66, v40, v4
	v_fma_f32 v5, v66, v44, v5
	v_fma_f32 v10, v67, v17, v10
	v_fma_f32 v11, v67, v21, v11
	v_fma_f32 v8, v67, v25, v8
	v_fma_f32 v9, v67, v29, v9
	v_fma_f32 v6, v67, v33, v6
	v_fma_f32 v7, v67, v37, v7
	v_fma_f32 v4, v67, v41, v4
	v_fma_f32 v5, v67, v45, v5
	global_load_dword v116, v[194:195], off
	v_lshl_add_u64 v[194:195], v[194:195], 0, s[0:1]
	global_load_dword v117, v[196:197], off
	v_lshl_add_u64 v[196:197], v[196:197], 0, s[0:1]
	global_load_dword v118, v[198:199], off
	v_lshl_add_u64 v[198:199], v[198:199], 0, s[0:1]
	global_load_dword v119, v[200:201], off
	v_lshl_add_u64 v[200:201], v[200:201], 0, s[0:1]
	ds_read_b128 v[14:17], v202 offset:32
	ds_read_b128 v[18:21], v202 offset:4128
	ds_read_b128 v[22:25], v202 offset:8224
	ds_read_b128 v[26:29], v202 offset:12320
	ds_read_b128 v[30:33], v202 offset:16416
	ds_read_b128 v[34:37], v202 offset:20512
	ds_read_b128 v[38:41], v202 offset:24608
	ds_read_b128 v[42:45], v202 offset:28704
	s_waitcnt vmcnt(48) lgkmcnt(8)
	v_fma_f32 v10, v68, v204, v10
	v_fma_f32 v11, v68, v208, v11
	v_fma_f32 v8, v68, v212, v8
	v_fma_f32 v9, v68, v216, v9
	v_fma_f32 v6, v68, v220, v6
	v_fma_f32 v7, v68, v224, v7
	v_fma_f32 v4, v68, v228, v4
	v_fma_f32 v5, v68, v232, v5
	v_fma_f32 v10, v69, v205, v10
	v_fma_f32 v11, v69, v209, v11
	v_fma_f32 v8, v69, v213, v8
	v_fma_f32 v9, v69, v217, v9
	v_fma_f32 v6, v69, v221, v6
	v_fma_f32 v7, v69, v225, v7
	v_fma_f32 v4, v69, v229, v4
	v_fma_f32 v5, v69, v233, v5
	v_fma_f32 v10, v70, v206, v10
	v_fma_f32 v11, v70, v210, v11
	v_fma_f32 v8, v70, v214, v8
	v_fma_f32 v9, v70, v218, v9
	v_fma_f32 v6, v70, v222, v6
	v_fma_f32 v7, v70, v226, v7
	v_fma_f32 v4, v70, v230, v4
	v_fma_f32 v5, v70, v234, v5
	v_fma_f32 v10, v71, v207, v10
	v_fma_f32 v11, v71, v211, v11
	v_fma_f32 v8, v71, v215, v8
	v_fma_f32 v9, v71, v219, v9
	v_fma_f32 v6, v71, v223, v6
	v_fma_f32 v7, v71, v227, v7
	v_fma_f32 v4, v71, v231, v4
	v_fma_f32 v5, v71, v235, v5
	global_load_dword v120, v[194:195], off
	v_lshl_add_u64 v[194:195], v[194:195], 0, s[0:1]
	global_load_dword v121, v[196:197], off
	v_lshl_add_u64 v[196:197], v[196:197], 0, s[0:1]
	global_load_dword v122, v[198:199], off
	v_lshl_add_u64 v[198:199], v[198:199], 0, s[0:1]
	global_load_dword v123, v[200:201], off
	v_lshl_add_u64 v[200:201], v[200:201], 0, s[0:1]
	ds_read_b128 v[204:207], v202 offset:48
	ds_read_b128 v[208:211], v202 offset:4144
	ds_read_b128 v[212:215], v202 offset:8240
	ds_read_b128 v[216:219], v202 offset:12336
	ds_read_b128 v[220:223], v202 offset:16432
	ds_read_b128 v[224:227], v202 offset:20528
	ds_read_b128 v[228:231], v202 offset:24624
	ds_read_b128 v[232:235], v202 offset:28720
	s_waitcnt vmcnt(48) lgkmcnt(8)
	v_fma_f32 v10, v72, v14, v10
	v_fma_f32 v11, v72, v18, v11
	v_fma_f32 v8, v72, v22, v8
	v_fma_f32 v9, v72, v26, v9
	v_fma_f32 v6, v72, v30, v6
	v_fma_f32 v7, v72, v34, v7
	v_fma_f32 v4, v72, v38, v4
	v_fma_f32 v5, v72, v42, v5
	v_fma_f32 v10, v73, v15, v10
	v_fma_f32 v11, v73, v19, v11
	v_fma_f32 v8, v73, v23, v8
	v_fma_f32 v9, v73, v27, v9
	v_fma_f32 v6, v73, v31, v6
	v_fma_f32 v7, v73, v35, v7
	v_fma_f32 v4, v73, v39, v4
	v_fma_f32 v5, v73, v43, v5
	v_fma_f32 v10, v74, v16, v10
	v_fma_f32 v11, v74, v20, v11
	v_fma_f32 v8, v74, v24, v8
	v_fma_f32 v9, v74, v28, v9
	v_fma_f32 v6, v74, v32, v6
	v_fma_f32 v7, v74, v36, v7
	v_fma_f32 v4, v74, v40, v4
	v_fma_f32 v5, v74, v44, v5
	v_fma_f32 v10, v75, v17, v10
	v_fma_f32 v11, v75, v21, v11
	v_fma_f32 v8, v75, v25, v8
	v_fma_f32 v9, v75, v29, v9
	v_fma_f32 v6, v75, v33, v6
	v_fma_f32 v7, v75, v37, v7
	v_fma_f32 v4, v75, v41, v4
	v_fma_f32 v5, v75, v45, v5
	global_load_dword v124, v[194:195], off
	v_lshl_add_u64 v[194:195], v[194:195], 0, s[0:1]
	global_load_dword v125, v[196:197], off
	v_lshl_add_u64 v[196:197], v[196:197], 0, s[0:1]
	global_load_dword v126, v[198:199], off
	v_lshl_add_u64 v[198:199], v[198:199], 0, s[0:1]
	global_load_dword v127, v[200:201], off
	v_lshl_add_u64 v[200:201], v[200:201], 0, s[0:1]
	ds_read_b128 v[14:17], v202 offset:64
	ds_read_b128 v[18:21], v202 offset:4160
	ds_read_b128 v[22:25], v202 offset:8256
	ds_read_b128 v[26:29], v202 offset:12352
	ds_read_b128 v[30:33], v202 offset:16448
	ds_read_b128 v[34:37], v202 offset:20544
	ds_read_b128 v[38:41], v202 offset:24640
	ds_read_b128 v[42:45], v202 offset:28736
	s_waitcnt vmcnt(48) lgkmcnt(8)
	v_fma_f32 v10, v76, v204, v10
	v_fma_f32 v11, v76, v208, v11
	v_fma_f32 v8, v76, v212, v8
	v_fma_f32 v9, v76, v216, v9
	v_fma_f32 v6, v76, v220, v6
	v_fma_f32 v7, v76, v224, v7
	v_fma_f32 v4, v76, v228, v4
	v_fma_f32 v5, v76, v232, v5
	v_fma_f32 v10, v77, v205, v10
	v_fma_f32 v11, v77, v209, v11
	v_fma_f32 v8, v77, v213, v8
	v_fma_f32 v9, v77, v217, v9
	v_fma_f32 v6, v77, v221, v6
	v_fma_f32 v7, v77, v225, v7
	v_fma_f32 v4, v77, v229, v4
	v_fma_f32 v5, v77, v233, v5
	v_fma_f32 v10, v78, v206, v10
	v_fma_f32 v11, v78, v210, v11
	v_fma_f32 v8, v78, v214, v8
	v_fma_f32 v9, v78, v218, v9
	v_fma_f32 v6, v78, v222, v6
	v_fma_f32 v7, v78, v226, v7
	v_fma_f32 v4, v78, v230, v4
	v_fma_f32 v5, v78, v234, v5
	v_fma_f32 v10, v79, v207, v10
	v_fma_f32 v11, v79, v211, v11
	v_fma_f32 v8, v79, v215, v8
	v_fma_f32 v9, v79, v219, v9
	v_fma_f32 v6, v79, v223, v6
	v_fma_f32 v7, v79, v227, v7
	v_fma_f32 v4, v79, v231, v4
	v_fma_f32 v5, v79, v235, v5
	global_load_dword v128, v[194:195], off
	v_lshl_add_u64 v[194:195], v[194:195], 0, s[0:1]
	global_load_dword v129, v[196:197], off
	v_lshl_add_u64 v[196:197], v[196:197], 0, s[0:1]
	global_load_dword v130, v[198:199], off
	v_lshl_add_u64 v[198:199], v[198:199], 0, s[0:1]
	global_load_dword v131, v[200:201], off
	v_lshl_add_u64 v[200:201], v[200:201], 0, s[0:1]
	ds_read_b128 v[204:207], v202 offset:80
	ds_read_b128 v[208:211], v202 offset:4176
	ds_read_b128 v[212:215], v202 offset:8272
	ds_read_b128 v[216:219], v202 offset:12368
	ds_read_b128 v[220:223], v202 offset:16464
	ds_read_b128 v[224:227], v202 offset:20560
	ds_read_b128 v[228:231], v202 offset:24656
	ds_read_b128 v[232:235], v202 offset:28752
	s_waitcnt vmcnt(48) lgkmcnt(8)
	v_fma_f32 v10, v80, v14, v10
	v_fma_f32 v11, v80, v18, v11
	v_fma_f32 v8, v80, v22, v8
	v_fma_f32 v9, v80, v26, v9
	v_fma_f32 v6, v80, v30, v6
	v_fma_f32 v7, v80, v34, v7
	v_fma_f32 v4, v80, v38, v4
	v_fma_f32 v5, v80, v42, v5
	v_fma_f32 v10, v81, v15, v10
	v_fma_f32 v11, v81, v19, v11
	v_fma_f32 v8, v81, v23, v8
	v_fma_f32 v9, v81, v27, v9
	v_fma_f32 v6, v81, v31, v6
	v_fma_f32 v7, v81, v35, v7
	v_fma_f32 v4, v81, v39, v4
	v_fma_f32 v5, v81, v43, v5
	v_fma_f32 v10, v82, v16, v10
	v_fma_f32 v11, v82, v20, v11
	v_fma_f32 v8, v82, v24, v8
	v_fma_f32 v9, v82, v28, v9
	v_fma_f32 v6, v82, v32, v6
	v_fma_f32 v7, v82, v36, v7
	v_fma_f32 v4, v82, v40, v4
	v_fma_f32 v5, v82, v44, v5
	v_fma_f32 v10, v83, v17, v10
	v_fma_f32 v11, v83, v21, v11
	v_fma_f32 v8, v83, v25, v8
	v_fma_f32 v9, v83, v29, v9
	v_fma_f32 v6, v83, v33, v6
	v_fma_f32 v7, v83, v37, v7
	v_fma_f32 v4, v83, v41, v4
	v_fma_f32 v5, v83, v45, v5
	global_load_dword v132, v[194:195], off
	v_lshl_add_u64 v[194:195], v[194:195], 0, s[0:1]
	global_load_dword v133, v[196:197], off
	v_lshl_add_u64 v[196:197], v[196:197], 0, s[0:1]
	global_load_dword v134, v[198:199], off
	v_lshl_add_u64 v[198:199], v[198:199], 0, s[0:1]
	global_load_dword v135, v[200:201], off
	v_lshl_add_u64 v[200:201], v[200:201], 0, s[0:1]
	ds_read_b128 v[14:17], v202 offset:96
	ds_read_b128 v[18:21], v202 offset:4192
	ds_read_b128 v[22:25], v202 offset:8288
	ds_read_b128 v[26:29], v202 offset:12384
	ds_read_b128 v[30:33], v202 offset:16480
	ds_read_b128 v[34:37], v202 offset:20576
	ds_read_b128 v[38:41], v202 offset:24672
	ds_read_b128 v[42:45], v202 offset:28768
	s_waitcnt vmcnt(48) lgkmcnt(8)
	v_fma_f32 v10, v84, v204, v10
	v_fma_f32 v11, v84, v208, v11
	v_fma_f32 v8, v84, v212, v8
	v_fma_f32 v9, v84, v216, v9
	v_fma_f32 v6, v84, v220, v6
	v_fma_f32 v7, v84, v224, v7
	v_fma_f32 v4, v84, v228, v4
	v_fma_f32 v5, v84, v232, v5
	v_fma_f32 v10, v85, v205, v10
	v_fma_f32 v11, v85, v209, v11
	v_fma_f32 v8, v85, v213, v8
	v_fma_f32 v9, v85, v217, v9
	v_fma_f32 v6, v85, v221, v6
	v_fma_f32 v7, v85, v225, v7
	v_fma_f32 v4, v85, v229, v4
	v_fma_f32 v5, v85, v233, v5
	v_fma_f32 v10, v86, v206, v10
	v_fma_f32 v11, v86, v210, v11
	v_fma_f32 v8, v86, v214, v8
	v_fma_f32 v9, v86, v218, v9
	v_fma_f32 v6, v86, v222, v6
	v_fma_f32 v7, v86, v226, v7
	v_fma_f32 v4, v86, v230, v4
	v_fma_f32 v5, v86, v234, v5
	v_fma_f32 v10, v87, v207, v10
	v_fma_f32 v11, v87, v211, v11
	v_fma_f32 v8, v87, v215, v8
	v_fma_f32 v9, v87, v219, v9
	v_fma_f32 v6, v87, v223, v6
	v_fma_f32 v7, v87, v227, v7
	v_fma_f32 v4, v87, v231, v4
	v_fma_f32 v5, v87, v235, v5
	global_load_dword v136, v[194:195], off
	v_lshl_add_u64 v[194:195], v[194:195], 0, s[0:1]
	global_load_dword v137, v[196:197], off
	v_lshl_add_u64 v[196:197], v[196:197], 0, s[0:1]
	global_load_dword v138, v[198:199], off
	v_lshl_add_u64 v[198:199], v[198:199], 0, s[0:1]
	global_load_dword v139, v[200:201], off
	v_lshl_add_u64 v[200:201], v[200:201], 0, s[0:1]
	ds_read_b128 v[204:207], v202 offset:112
	ds_read_b128 v[208:211], v202 offset:4208
	ds_read_b128 v[212:215], v202 offset:8304
	ds_read_b128 v[216:219], v202 offset:12400
	ds_read_b128 v[220:223], v202 offset:16496
	ds_read_b128 v[224:227], v202 offset:20592
	ds_read_b128 v[228:231], v202 offset:24688
	ds_read_b128 v[232:235], v202 offset:28784
	s_waitcnt vmcnt(48) lgkmcnt(8)
	v_fma_f32 v10, v88, v14, v10
	v_fma_f32 v11, v88, v18, v11
	v_fma_f32 v8, v88, v22, v8
	v_fma_f32 v9, v88, v26, v9
	v_fma_f32 v6, v88, v30, v6
	v_fma_f32 v7, v88, v34, v7
	v_fma_f32 v4, v88, v38, v4
	v_fma_f32 v5, v88, v42, v5
	v_fma_f32 v10, v89, v15, v10
	v_fma_f32 v11, v89, v19, v11
	v_fma_f32 v8, v89, v23, v8
	v_fma_f32 v9, v89, v27, v9
	v_fma_f32 v6, v89, v31, v6
	v_fma_f32 v7, v89, v35, v7
	v_fma_f32 v4, v89, v39, v4
	v_fma_f32 v5, v89, v43, v5
	v_fma_f32 v10, v90, v16, v10
	v_fma_f32 v11, v90, v20, v11
	v_fma_f32 v8, v90, v24, v8
	v_fma_f32 v9, v90, v28, v9
	v_fma_f32 v6, v90, v32, v6
	v_fma_f32 v7, v90, v36, v7
	v_fma_f32 v4, v90, v40, v4
	v_fma_f32 v5, v90, v44, v5
	v_fma_f32 v10, v91, v17, v10
	v_fma_f32 v11, v91, v21, v11
	v_fma_f32 v8, v91, v25, v8
	v_fma_f32 v9, v91, v29, v9
	v_fma_f32 v6, v91, v33, v6
	v_fma_f32 v7, v91, v37, v7
	v_fma_f32 v4, v91, v41, v4
	v_fma_f32 v5, v91, v45, v5
	global_load_dword v140, v[194:195], off
	v_lshl_add_u64 v[194:195], v[194:195], 0, s[0:1]
	global_load_dword v141, v[196:197], off
	v_lshl_add_u64 v[196:197], v[196:197], 0, s[0:1]
	global_load_dword v142, v[198:199], off
	v_lshl_add_u64 v[198:199], v[198:199], 0, s[0:1]
	global_load_dword v143, v[200:201], off
	v_lshl_add_u64 v[200:201], v[200:201], 0, s[0:1]
	ds_read_b128 v[14:17], v202 offset:128
	ds_read_b128 v[18:21], v202 offset:4224
	ds_read_b128 v[22:25], v202 offset:8320
	ds_read_b128 v[26:29], v202 offset:12416
	ds_read_b128 v[30:33], v202 offset:16512
	ds_read_b128 v[34:37], v202 offset:20608
	ds_read_b128 v[38:41], v202 offset:24704
	ds_read_b128 v[42:45], v202 offset:28800
	s_waitcnt vmcnt(48) lgkmcnt(8)
	v_fma_f32 v10, v92, v204, v10
	v_fma_f32 v11, v92, v208, v11
	v_fma_f32 v8, v92, v212, v8
	v_fma_f32 v9, v92, v216, v9
	v_fma_f32 v6, v92, v220, v6
	v_fma_f32 v7, v92, v224, v7
	v_fma_f32 v4, v92, v228, v4
	v_fma_f32 v5, v92, v232, v5
	v_fma_f32 v10, v93, v205, v10
	v_fma_f32 v11, v93, v209, v11
	v_fma_f32 v8, v93, v213, v8
	v_fma_f32 v9, v93, v217, v9
	v_fma_f32 v6, v93, v221, v6
	v_fma_f32 v7, v93, v225, v7
	v_fma_f32 v4, v93, v229, v4
	v_fma_f32 v5, v93, v233, v5
	v_fma_f32 v10, v94, v206, v10
	v_fma_f32 v11, v94, v210, v11
	v_fma_f32 v8, v94, v214, v8
	v_fma_f32 v9, v94, v218, v9
	v_fma_f32 v6, v94, v222, v6
	v_fma_f32 v7, v94, v226, v7
	v_fma_f32 v4, v94, v230, v4
	v_fma_f32 v5, v94, v234, v5
	v_fma_f32 v10, v95, v207, v10
	v_fma_f32 v11, v95, v211, v11
	v_fma_f32 v8, v95, v215, v8
	v_fma_f32 v9, v95, v219, v9
	v_fma_f32 v6, v95, v223, v6
	v_fma_f32 v7, v95, v227, v7
	v_fma_f32 v4, v95, v231, v4
	v_fma_f32 v5, v95, v235, v5
	global_load_dword v144, v[194:195], off
	v_lshl_add_u64 v[194:195], v[194:195], 0, s[0:1]
	global_load_dword v145, v[196:197], off
	v_lshl_add_u64 v[196:197], v[196:197], 0, s[0:1]
	global_load_dword v146, v[198:199], off
	v_lshl_add_u64 v[198:199], v[198:199], 0, s[0:1]
	global_load_dword v147, v[200:201], off
	v_lshl_add_u64 v[200:201], v[200:201], 0, s[0:1]
	ds_read_b128 v[204:207], v202 offset:144
	ds_read_b128 v[208:211], v202 offset:4240
	ds_read_b128 v[212:215], v202 offset:8336
	ds_read_b128 v[216:219], v202 offset:12432
	ds_read_b128 v[220:223], v202 offset:16528
	ds_read_b128 v[224:227], v202 offset:20624
	ds_read_b128 v[228:231], v202 offset:24720
	ds_read_b128 v[232:235], v202 offset:28816
	s_waitcnt vmcnt(48) lgkmcnt(8)
	v_fma_f32 v10, v96, v14, v10
	v_fma_f32 v11, v96, v18, v11
	v_fma_f32 v8, v96, v22, v8
	v_fma_f32 v9, v96, v26, v9
	v_fma_f32 v6, v96, v30, v6
	v_fma_f32 v7, v96, v34, v7
	v_fma_f32 v4, v96, v38, v4
	v_fma_f32 v5, v96, v42, v5
	v_fma_f32 v10, v97, v15, v10
	v_fma_f32 v11, v97, v19, v11
	v_fma_f32 v8, v97, v23, v8
	v_fma_f32 v9, v97, v27, v9
	v_fma_f32 v6, v97, v31, v6
	v_fma_f32 v7, v97, v35, v7
	v_fma_f32 v4, v97, v39, v4
	v_fma_f32 v5, v97, v43, v5
	v_fma_f32 v10, v98, v16, v10
	v_fma_f32 v11, v98, v20, v11
	v_fma_f32 v8, v98, v24, v8
	v_fma_f32 v9, v98, v28, v9
	v_fma_f32 v6, v98, v32, v6
	v_fma_f32 v7, v98, v36, v7
	v_fma_f32 v4, v98, v40, v4
	v_fma_f32 v5, v98, v44, v5
	v_fma_f32 v10, v99, v17, v10
	v_fma_f32 v11, v99, v21, v11
	v_fma_f32 v8, v99, v25, v8
	v_fma_f32 v9, v99, v29, v9
	v_fma_f32 v6, v99, v33, v6
	v_fma_f32 v7, v99, v37, v7
	v_fma_f32 v4, v99, v41, v4
	v_fma_f32 v5, v99, v45, v5
	global_load_dword v148, v[194:195], off
	v_lshl_add_u64 v[194:195], v[194:195], 0, s[0:1]
	global_load_dword v149, v[196:197], off
	v_lshl_add_u64 v[196:197], v[196:197], 0, s[0:1]
	global_load_dword v150, v[198:199], off
	v_lshl_add_u64 v[198:199], v[198:199], 0, s[0:1]
	global_load_dword v151, v[200:201], off
	v_lshl_add_u64 v[200:201], v[200:201], 0, s[0:1]
	ds_read_b128 v[14:17], v202 offset:160
	ds_read_b128 v[18:21], v202 offset:4256
	ds_read_b128 v[22:25], v202 offset:8352
	ds_read_b128 v[26:29], v202 offset:12448
	ds_read_b128 v[30:33], v202 offset:16544
	ds_read_b128 v[34:37], v202 offset:20640
	ds_read_b128 v[38:41], v202 offset:24736
	ds_read_b128 v[42:45], v202 offset:28832
	s_waitcnt vmcnt(48) lgkmcnt(8)
	v_fma_f32 v10, v100, v204, v10
	v_fma_f32 v11, v100, v208, v11
	v_fma_f32 v8, v100, v212, v8
	v_fma_f32 v9, v100, v216, v9
	v_fma_f32 v6, v100, v220, v6
	v_fma_f32 v7, v100, v224, v7
	v_fma_f32 v4, v100, v228, v4
	v_fma_f32 v5, v100, v232, v5
	v_fma_f32 v10, v101, v205, v10
	v_fma_f32 v11, v101, v209, v11
	v_fma_f32 v8, v101, v213, v8
	v_fma_f32 v9, v101, v217, v9
	v_fma_f32 v6, v101, v221, v6
	v_fma_f32 v7, v101, v225, v7
	v_fma_f32 v4, v101, v229, v4
	v_fma_f32 v5, v101, v233, v5
	v_fma_f32 v10, v102, v206, v10
	v_fma_f32 v11, v102, v210, v11
	v_fma_f32 v8, v102, v214, v8
	v_fma_f32 v9, v102, v218, v9
	v_fma_f32 v6, v102, v222, v6
	v_fma_f32 v7, v102, v226, v7
	v_fma_f32 v4, v102, v230, v4
	v_fma_f32 v5, v102, v234, v5
	v_fma_f32 v10, v103, v207, v10
	v_fma_f32 v11, v103, v211, v11
	v_fma_f32 v8, v103, v215, v8
	v_fma_f32 v9, v103, v219, v9
	v_fma_f32 v6, v103, v223, v6
	v_fma_f32 v7, v103, v227, v7
	v_fma_f32 v4, v103, v231, v4
	v_fma_f32 v5, v103, v235, v5
	global_load_dword v152, v[194:195], off
	v_lshl_add_u64 v[194:195], v[194:195], 0, s[0:1]
	global_load_dword v153, v[196:197], off
	v_lshl_add_u64 v[196:197], v[196:197], 0, s[0:1]
	global_load_dword v154, v[198:199], off
	v_lshl_add_u64 v[198:199], v[198:199], 0, s[0:1]
	global_load_dword v155, v[200:201], off
	v_lshl_add_u64 v[200:201], v[200:201], 0, s[0:1]
	ds_read_b128 v[204:207], v202 offset:176
	ds_read_b128 v[208:211], v202 offset:4272
	ds_read_b128 v[212:215], v202 offset:8368
	ds_read_b128 v[216:219], v202 offset:12464
	ds_read_b128 v[220:223], v202 offset:16560
	ds_read_b128 v[224:227], v202 offset:20656
	ds_read_b128 v[228:231], v202 offset:24752
	ds_read_b128 v[232:235], v202 offset:28848
	s_waitcnt vmcnt(48) lgkmcnt(8)
	v_fma_f32 v10, v104, v14, v10
	v_fma_f32 v11, v104, v18, v11
	v_fma_f32 v8, v104, v22, v8
	v_fma_f32 v9, v104, v26, v9
	v_fma_f32 v6, v104, v30, v6
	v_fma_f32 v7, v104, v34, v7
	v_fma_f32 v4, v104, v38, v4
	v_fma_f32 v5, v104, v42, v5
	v_fma_f32 v10, v105, v15, v10
	v_fma_f32 v11, v105, v19, v11
	v_fma_f32 v8, v105, v23, v8
	v_fma_f32 v9, v105, v27, v9
	v_fma_f32 v6, v105, v31, v6
	v_fma_f32 v7, v105, v35, v7
	v_fma_f32 v4, v105, v39, v4
	v_fma_f32 v5, v105, v43, v5
	v_fma_f32 v10, v106, v16, v10
	v_fma_f32 v11, v106, v20, v11
	v_fma_f32 v8, v106, v24, v8
	v_fma_f32 v9, v106, v28, v9
	v_fma_f32 v6, v106, v32, v6
	v_fma_f32 v7, v106, v36, v7
	v_fma_f32 v4, v106, v40, v4
	v_fma_f32 v5, v106, v44, v5
	v_fma_f32 v10, v107, v17, v10
	v_fma_f32 v11, v107, v21, v11
	v_fma_f32 v8, v107, v25, v8
	v_fma_f32 v9, v107, v29, v9
	v_fma_f32 v6, v107, v33, v6
	v_fma_f32 v7, v107, v37, v7
	v_fma_f32 v4, v107, v41, v4
	v_fma_f32 v5, v107, v45, v5
	global_load_dword v156, v[194:195], off
	v_lshl_add_u64 v[194:195], v[194:195], 0, s[0:1]
	global_load_dword v157, v[196:197], off
	v_lshl_add_u64 v[196:197], v[196:197], 0, s[0:1]
	global_load_dword v158, v[198:199], off
	v_lshl_add_u64 v[198:199], v[198:199], 0, s[0:1]
	global_load_dword v159, v[200:201], off
	v_lshl_add_u64 v[200:201], v[200:201], 0, s[0:1]
	ds_read_b128 v[14:17], v202 offset:192
	ds_read_b128 v[18:21], v202 offset:4288
	ds_read_b128 v[22:25], v202 offset:8384
	ds_read_b128 v[26:29], v202 offset:12480
	ds_read_b128 v[30:33], v202 offset:16576
	ds_read_b128 v[34:37], v202 offset:20672
	ds_read_b128 v[38:41], v202 offset:24768
	ds_read_b128 v[42:45], v202 offset:28864
	s_waitcnt vmcnt(48) lgkmcnt(8)
	v_fma_f32 v10, v108, v204, v10
	v_fma_f32 v11, v108, v208, v11
	v_fma_f32 v8, v108, v212, v8
	v_fma_f32 v9, v108, v216, v9
	v_fma_f32 v6, v108, v220, v6
	v_fma_f32 v7, v108, v224, v7
	v_fma_f32 v4, v108, v228, v4
	v_fma_f32 v5, v108, v232, v5
	v_fma_f32 v10, v109, v205, v10
	v_fma_f32 v11, v109, v209, v11
	v_fma_f32 v8, v109, v213, v8
	v_fma_f32 v9, v109, v217, v9
	v_fma_f32 v6, v109, v221, v6
	v_fma_f32 v7, v109, v225, v7
	v_fma_f32 v4, v109, v229, v4
	v_fma_f32 v5, v109, v233, v5
	v_fma_f32 v10, v110, v206, v10
	v_fma_f32 v11, v110, v210, v11
	v_fma_f32 v8, v110, v214, v8
	v_fma_f32 v9, v110, v218, v9
	v_fma_f32 v6, v110, v222, v6
	v_fma_f32 v7, v110, v226, v7
	v_fma_f32 v4, v110, v230, v4
	v_fma_f32 v5, v110, v234, v5
	v_fma_f32 v10, v111, v207, v10
	v_fma_f32 v11, v111, v211, v11
	v_fma_f32 v8, v111, v215, v8
	v_fma_f32 v9, v111, v219, v9
	v_fma_f32 v6, v111, v223, v6
	v_fma_f32 v7, v111, v227, v7
	v_fma_f32 v4, v111, v231, v4
	v_fma_f32 v5, v111, v235, v5
	global_load_dword v160, v[194:195], off
	v_lshl_add_u64 v[194:195], v[194:195], 0, s[0:1]
	global_load_dword v161, v[196:197], off
	v_lshl_add_u64 v[196:197], v[196:197], 0, s[0:1]
	global_load_dword v162, v[198:199], off
	v_lshl_add_u64 v[198:199], v[198:199], 0, s[0:1]
	global_load_dword v163, v[200:201], off
	v_lshl_add_u64 v[200:201], v[200:201], 0, s[0:1]
	ds_read_b128 v[204:207], v202 offset:208
	ds_read_b128 v[208:211], v202 offset:4304
	ds_read_b128 v[212:215], v202 offset:8400
	ds_read_b128 v[216:219], v202 offset:12496
	ds_read_b128 v[220:223], v202 offset:16592
	ds_read_b128 v[224:227], v202 offset:20688
	ds_read_b128 v[228:231], v202 offset:24784
	ds_read_b128 v[232:235], v202 offset:28880
	s_waitcnt vmcnt(48) lgkmcnt(8)
	v_fma_f32 v10, v112, v14, v10
	v_fma_f32 v11, v112, v18, v11
	v_fma_f32 v8, v112, v22, v8
	v_fma_f32 v9, v112, v26, v9
	v_fma_f32 v6, v112, v30, v6
	v_fma_f32 v7, v112, v34, v7
	v_fma_f32 v4, v112, v38, v4
	v_fma_f32 v5, v112, v42, v5
	v_fma_f32 v10, v113, v15, v10
	v_fma_f32 v11, v113, v19, v11
	v_fma_f32 v8, v113, v23, v8
	v_fma_f32 v9, v113, v27, v9
	v_fma_f32 v6, v113, v31, v6
	v_fma_f32 v7, v113, v35, v7
	v_fma_f32 v4, v113, v39, v4
	v_fma_f32 v5, v113, v43, v5
	v_fma_f32 v10, v114, v16, v10
	v_fma_f32 v11, v114, v20, v11
	v_fma_f32 v8, v114, v24, v8
	v_fma_f32 v9, v114, v28, v9
	v_fma_f32 v6, v114, v32, v6
	v_fma_f32 v7, v114, v36, v7
	v_fma_f32 v4, v114, v40, v4
	v_fma_f32 v5, v114, v44, v5
	v_fma_f32 v10, v115, v17, v10
	v_fma_f32 v11, v115, v21, v11
	v_fma_f32 v8, v115, v25, v8
	v_fma_f32 v9, v115, v29, v9
	v_fma_f32 v6, v115, v33, v6
	v_fma_f32 v7, v115, v37, v7
	v_fma_f32 v4, v115, v41, v4
	v_fma_f32 v5, v115, v45, v5
	global_load_dword v164, v[194:195], off
	v_lshl_add_u64 v[194:195], v[194:195], 0, s[0:1]
	global_load_dword v165, v[196:197], off
	v_lshl_add_u64 v[196:197], v[196:197], 0, s[0:1]
	global_load_dword v166, v[198:199], off
	v_lshl_add_u64 v[198:199], v[198:199], 0, s[0:1]
	global_load_dword v167, v[200:201], off
	v_lshl_add_u64 v[200:201], v[200:201], 0, s[0:1]
	ds_read_b128 v[14:17], v202 offset:224
	ds_read_b128 v[18:21], v202 offset:4320
	ds_read_b128 v[22:25], v202 offset:8416
	ds_read_b128 v[26:29], v202 offset:12512
	ds_read_b128 v[30:33], v202 offset:16608
	ds_read_b128 v[34:37], v202 offset:20704
	ds_read_b128 v[38:41], v202 offset:24800
	ds_read_b128 v[42:45], v202 offset:28896
	s_waitcnt vmcnt(48) lgkmcnt(8)
	v_fma_f32 v10, v116, v204, v10
	v_fma_f32 v11, v116, v208, v11
	v_fma_f32 v8, v116, v212, v8
	v_fma_f32 v9, v116, v216, v9
	v_fma_f32 v6, v116, v220, v6
	v_fma_f32 v7, v116, v224, v7
	v_fma_f32 v4, v116, v228, v4
	v_fma_f32 v5, v116, v232, v5
	v_fma_f32 v10, v117, v205, v10
	v_fma_f32 v11, v117, v209, v11
	v_fma_f32 v8, v117, v213, v8
	v_fma_f32 v9, v117, v217, v9
	v_fma_f32 v6, v117, v221, v6
	v_fma_f32 v7, v117, v225, v7
	v_fma_f32 v4, v117, v229, v4
	v_fma_f32 v5, v117, v233, v5
	v_fma_f32 v10, v118, v206, v10
	v_fma_f32 v11, v118, v210, v11
	v_fma_f32 v8, v118, v214, v8
	v_fma_f32 v9, v118, v218, v9
	v_fma_f32 v6, v118, v222, v6
	v_fma_f32 v7, v118, v226, v7
	v_fma_f32 v4, v118, v230, v4
	v_fma_f32 v5, v118, v234, v5
	v_fma_f32 v10, v119, v207, v10
	v_fma_f32 v11, v119, v211, v11
	v_fma_f32 v8, v119, v215, v8
	v_fma_f32 v9, v119, v219, v9
	v_fma_f32 v6, v119, v223, v6
	v_fma_f32 v7, v119, v227, v7
	v_fma_f32 v4, v119, v231, v4
	v_fma_f32 v5, v119, v235, v5
	global_load_dword v168, v[194:195], off
	v_lshl_add_u64 v[194:195], v[194:195], 0, s[0:1]
	global_load_dword v169, v[196:197], off
	v_lshl_add_u64 v[196:197], v[196:197], 0, s[0:1]
	global_load_dword v170, v[198:199], off
	v_lshl_add_u64 v[198:199], v[198:199], 0, s[0:1]
	global_load_dword v171, v[200:201], off
	v_lshl_add_u64 v[200:201], v[200:201], 0, s[0:1]
	ds_read_b128 v[204:207], v202 offset:240
	ds_read_b128 v[208:211], v202 offset:4336
	ds_read_b128 v[212:215], v202 offset:8432
	ds_read_b128 v[216:219], v202 offset:12528
	ds_read_b128 v[220:223], v202 offset:16624
	ds_read_b128 v[224:227], v202 offset:20720
	ds_read_b128 v[228:231], v202 offset:24816
	ds_read_b128 v[232:235], v202 offset:28912
	s_waitcnt vmcnt(48) lgkmcnt(8)
	v_fma_f32 v10, v120, v14, v10
	v_fma_f32 v11, v120, v18, v11
	v_fma_f32 v8, v120, v22, v8
	v_fma_f32 v9, v120, v26, v9
	v_fma_f32 v6, v120, v30, v6
	v_fma_f32 v7, v120, v34, v7
	v_fma_f32 v4, v120, v38, v4
	v_fma_f32 v5, v120, v42, v5
	v_fma_f32 v10, v121, v15, v10
	v_fma_f32 v11, v121, v19, v11
	v_fma_f32 v8, v121, v23, v8
	v_fma_f32 v9, v121, v27, v9
	v_fma_f32 v6, v121, v31, v6
	v_fma_f32 v7, v121, v35, v7
	v_fma_f32 v4, v121, v39, v4
	v_fma_f32 v5, v121, v43, v5
	v_fma_f32 v10, v122, v16, v10
	v_fma_f32 v11, v122, v20, v11
	v_fma_f32 v8, v122, v24, v8
	v_fma_f32 v9, v122, v28, v9
	v_fma_f32 v6, v122, v32, v6
	v_fma_f32 v7, v122, v36, v7
	v_fma_f32 v4, v122, v40, v4
	v_fma_f32 v5, v122, v44, v5
	v_fma_f32 v10, v123, v17, v10
	v_fma_f32 v11, v123, v21, v11
	v_fma_f32 v8, v123, v25, v8
	v_fma_f32 v9, v123, v29, v9
	v_fma_f32 v6, v123, v33, v6
	v_fma_f32 v7, v123, v37, v7
	v_fma_f32 v4, v123, v41, v4
	v_fma_f32 v5, v123, v45, v5
	global_load_dword v172, v[194:195], off
	v_lshl_add_u64 v[194:195], v[194:195], 0, s[0:1]
	global_load_dword v173, v[196:197], off
	v_lshl_add_u64 v[196:197], v[196:197], 0, s[0:1]
	global_load_dword v174, v[198:199], off
	v_lshl_add_u64 v[198:199], v[198:199], 0, s[0:1]
	global_load_dword v175, v[200:201], off
	v_lshl_add_u64 v[200:201], v[200:201], 0, s[0:1]
	ds_read_b128 v[14:17], v202 offset:256
	ds_read_b128 v[18:21], v202 offset:4352
	ds_read_b128 v[22:25], v202 offset:8448
	ds_read_b128 v[26:29], v202 offset:12544
	ds_read_b128 v[30:33], v202 offset:16640
	ds_read_b128 v[34:37], v202 offset:20736
	ds_read_b128 v[38:41], v202 offset:24832
	ds_read_b128 v[42:45], v202 offset:28928
	s_waitcnt vmcnt(48) lgkmcnt(8)
	v_fma_f32 v10, v124, v204, v10
	v_fma_f32 v11, v124, v208, v11
	v_fma_f32 v8, v124, v212, v8
	v_fma_f32 v9, v124, v216, v9
	v_fma_f32 v6, v124, v220, v6
	v_fma_f32 v7, v124, v224, v7
	v_fma_f32 v4, v124, v228, v4
	v_fma_f32 v5, v124, v232, v5
	v_fma_f32 v10, v125, v205, v10
	v_fma_f32 v11, v125, v209, v11
	v_fma_f32 v8, v125, v213, v8
	v_fma_f32 v9, v125, v217, v9
	v_fma_f32 v6, v125, v221, v6
	v_fma_f32 v7, v125, v225, v7
	v_fma_f32 v4, v125, v229, v4
	v_fma_f32 v5, v125, v233, v5
	v_fma_f32 v10, v126, v206, v10
	v_fma_f32 v11, v126, v210, v11
	v_fma_f32 v8, v126, v214, v8
	v_fma_f32 v9, v126, v218, v9
	v_fma_f32 v6, v126, v222, v6
	v_fma_f32 v7, v126, v226, v7
	v_fma_f32 v4, v126, v230, v4
	v_fma_f32 v5, v126, v234, v5
	v_fma_f32 v10, v127, v207, v10
	v_fma_f32 v11, v127, v211, v11
	v_fma_f32 v8, v127, v215, v8
	v_fma_f32 v9, v127, v219, v9
	v_fma_f32 v6, v127, v223, v6
	v_fma_f32 v7, v127, v227, v7
	v_fma_f32 v4, v127, v231, v4
	v_fma_f32 v5, v127, v235, v5
	global_load_dword v176, v[194:195], off
	v_lshl_add_u64 v[194:195], v[194:195], 0, s[0:1]
	global_load_dword v177, v[196:197], off
	v_lshl_add_u64 v[196:197], v[196:197], 0, s[0:1]
	global_load_dword v178, v[198:199], off
	v_lshl_add_u64 v[198:199], v[198:199], 0, s[0:1]
	global_load_dword v180, v[200:201], off
	v_lshl_add_u64 v[200:201], v[200:201], 0, s[0:1]
	ds_read_b128 v[204:207], v202 offset:272
	ds_read_b128 v[208:211], v202 offset:4368
	ds_read_b128 v[212:215], v202 offset:8464
	ds_read_b128 v[216:219], v202 offset:12560
	ds_read_b128 v[220:223], v202 offset:16656
	ds_read_b128 v[224:227], v202 offset:20752
	ds_read_b128 v[228:231], v202 offset:24848
	ds_read_b128 v[232:235], v202 offset:28944
	s_waitcnt vmcnt(48) lgkmcnt(8)
	v_fma_f32 v10, v128, v14, v10
	v_fma_f32 v11, v128, v18, v11
	v_fma_f32 v8, v128, v22, v8
	v_fma_f32 v9, v128, v26, v9
	v_fma_f32 v6, v128, v30, v6
	v_fma_f32 v7, v128, v34, v7
	v_fma_f32 v4, v128, v38, v4
	v_fma_f32 v5, v128, v42, v5
	v_fma_f32 v10, v129, v15, v10
	v_fma_f32 v11, v129, v19, v11
	v_fma_f32 v8, v129, v23, v8
	v_fma_f32 v9, v129, v27, v9
	v_fma_f32 v6, v129, v31, v6
	v_fma_f32 v7, v129, v35, v7
	v_fma_f32 v4, v129, v39, v4
	v_fma_f32 v5, v129, v43, v5
	v_fma_f32 v10, v130, v16, v10
	v_fma_f32 v11, v130, v20, v11
	v_fma_f32 v8, v130, v24, v8
	v_fma_f32 v9, v130, v28, v9
	v_fma_f32 v6, v130, v32, v6
	v_fma_f32 v7, v130, v36, v7
	v_fma_f32 v4, v130, v40, v4
	v_fma_f32 v5, v130, v44, v5
	v_fma_f32 v10, v131, v17, v10
	v_fma_f32 v11, v131, v21, v11
	v_fma_f32 v8, v131, v25, v8
	v_fma_f32 v9, v131, v29, v9
	v_fma_f32 v6, v131, v33, v6
	v_fma_f32 v7, v131, v37, v7
	v_fma_f32 v4, v131, v41, v4
	v_fma_f32 v5, v131, v45, v5
	global_load_dword v181, v[194:195], off
	v_lshl_add_u64 v[194:195], v[194:195], 0, s[0:1]
	global_load_dword v182, v[196:197], off
	v_lshl_add_u64 v[196:197], v[196:197], 0, s[0:1]
	global_load_dword v183, v[198:199], off
	v_lshl_add_u64 v[198:199], v[198:199], 0, s[0:1]
	global_load_dword v184, v[200:201], off
	v_lshl_add_u64 v[200:201], v[200:201], 0, s[0:1]
	ds_read_b128 v[14:17], v202 offset:288
	ds_read_b128 v[18:21], v202 offset:4384
	ds_read_b128 v[22:25], v202 offset:8480
	ds_read_b128 v[26:29], v202 offset:12576
	ds_read_b128 v[30:33], v202 offset:16672
	ds_read_b128 v[34:37], v202 offset:20768
	ds_read_b128 v[38:41], v202 offset:24864
	ds_read_b128 v[42:45], v202 offset:28960
	s_waitcnt vmcnt(48) lgkmcnt(8)
	v_fma_f32 v10, v132, v204, v10
	v_fma_f32 v11, v132, v208, v11
	v_fma_f32 v8, v132, v212, v8
	v_fma_f32 v9, v132, v216, v9
	v_fma_f32 v6, v132, v220, v6
	v_fma_f32 v7, v132, v224, v7
	v_fma_f32 v4, v132, v228, v4
	v_fma_f32 v5, v132, v232, v5
	v_fma_f32 v10, v133, v205, v10
	v_fma_f32 v11, v133, v209, v11
	v_fma_f32 v8, v133, v213, v8
	v_fma_f32 v9, v133, v217, v9
	v_fma_f32 v6, v133, v221, v6
	v_fma_f32 v7, v133, v225, v7
	v_fma_f32 v4, v133, v229, v4
	v_fma_f32 v5, v133, v233, v5
	v_fma_f32 v10, v134, v206, v10
	v_fma_f32 v11, v134, v210, v11
	v_fma_f32 v8, v134, v214, v8
	v_fma_f32 v9, v134, v218, v9
	v_fma_f32 v6, v134, v222, v6
	v_fma_f32 v7, v134, v226, v7
	v_fma_f32 v4, v134, v230, v4
	v_fma_f32 v5, v134, v234, v5
	v_fma_f32 v10, v135, v207, v10
	v_fma_f32 v11, v135, v211, v11
	v_fma_f32 v8, v135, v215, v8
	v_fma_f32 v9, v135, v219, v9
	v_fma_f32 v6, v135, v223, v6
	v_fma_f32 v7, v135, v227, v7
	v_fma_f32 v4, v135, v231, v4
	v_fma_f32 v5, v135, v235, v5
	global_load_dword v185, v[194:195], off
	v_lshl_add_u64 v[194:195], v[194:195], 0, s[0:1]
	global_load_dword v186, v[196:197], off
	v_lshl_add_u64 v[196:197], v[196:197], 0, s[0:1]
	global_load_dword v187, v[198:199], off
	v_lshl_add_u64 v[198:199], v[198:199], 0, s[0:1]
	global_load_dword v188, v[200:201], off
	v_lshl_add_u64 v[200:201], v[200:201], 0, s[0:1]
	ds_read_b128 v[204:207], v202 offset:304
	ds_read_b128 v[208:211], v202 offset:4400
	ds_read_b128 v[212:215], v202 offset:8496
	ds_read_b128 v[216:219], v202 offset:12592
	ds_read_b128 v[220:223], v202 offset:16688
	ds_read_b128 v[224:227], v202 offset:20784
	ds_read_b128 v[228:231], v202 offset:24880
	ds_read_b128 v[232:235], v202 offset:28976
	s_waitcnt vmcnt(48) lgkmcnt(8)
	v_fma_f32 v10, v136, v14, v10
	v_fma_f32 v11, v136, v18, v11
	v_fma_f32 v8, v136, v22, v8
	v_fma_f32 v9, v136, v26, v9
	v_fma_f32 v6, v136, v30, v6
	v_fma_f32 v7, v136, v34, v7
	v_fma_f32 v4, v136, v38, v4
	v_fma_f32 v5, v136, v42, v5
	v_fma_f32 v10, v137, v15, v10
	v_fma_f32 v11, v137, v19, v11
	v_fma_f32 v8, v137, v23, v8
	v_fma_f32 v9, v137, v27, v9
	v_fma_f32 v6, v137, v31, v6
	v_fma_f32 v7, v137, v35, v7
	v_fma_f32 v4, v137, v39, v4
	v_fma_f32 v5, v137, v43, v5
	v_fma_f32 v10, v138, v16, v10
	v_fma_f32 v11, v138, v20, v11
	v_fma_f32 v8, v138, v24, v8
	v_fma_f32 v9, v138, v28, v9
	v_fma_f32 v6, v138, v32, v6
	v_fma_f32 v7, v138, v36, v7
	v_fma_f32 v4, v138, v40, v4
	v_fma_f32 v5, v138, v44, v5
	v_fma_f32 v10, v139, v17, v10
	v_fma_f32 v11, v139, v21, v11
	v_fma_f32 v8, v139, v25, v8
	v_fma_f32 v9, v139, v29, v9
	v_fma_f32 v6, v139, v33, v6
	v_fma_f32 v7, v139, v37, v7
	v_fma_f32 v4, v139, v41, v4
	v_fma_f32 v5, v139, v45, v5
	global_load_dword v189, v[194:195], off
	global_load_dword v190, v[196:197], off
	global_load_dword v191, v[198:199], off
	global_load_dword v192, v[200:201], off
	ds_read_b128 v[14:17], v202 offset:320
	ds_read_b128 v[18:21], v202 offset:4416
	ds_read_b128 v[22:25], v202 offset:8512
	ds_read_b128 v[26:29], v202 offset:12608
	ds_read_b128 v[30:33], v202 offset:16704
	ds_read_b128 v[34:37], v202 offset:20800
	ds_read_b128 v[38:41], v202 offset:24896
	ds_read_b128 v[42:45], v202 offset:28992
	s_waitcnt vmcnt(48) lgkmcnt(8)
	v_fma_f32 v10, v140, v204, v10
	v_fma_f32 v11, v140, v208, v11
	v_fma_f32 v8, v140, v212, v8
	v_fma_f32 v9, v140, v216, v9
	v_fma_f32 v6, v140, v220, v6
	v_fma_f32 v7, v140, v224, v7
	v_fma_f32 v4, v140, v228, v4
	v_fma_f32 v5, v140, v232, v5
	v_fma_f32 v10, v141, v205, v10
	v_fma_f32 v11, v141, v209, v11
	v_fma_f32 v8, v141, v213, v8
	v_fma_f32 v9, v141, v217, v9
	v_fma_f32 v6, v141, v221, v6
	v_fma_f32 v7, v141, v225, v7
	v_fma_f32 v4, v141, v229, v4
	v_fma_f32 v5, v141, v233, v5
	v_fma_f32 v10, v142, v206, v10
	v_fma_f32 v11, v142, v210, v11
	v_fma_f32 v8, v142, v214, v8
	v_fma_f32 v9, v142, v218, v9
	v_fma_f32 v6, v142, v222, v6
	v_fma_f32 v7, v142, v226, v7
	v_fma_f32 v4, v142, v230, v4
	v_fma_f32 v5, v142, v234, v5
	v_fma_f32 v10, v143, v207, v10
	v_fma_f32 v11, v143, v211, v11
	v_fma_f32 v8, v143, v215, v8
	v_fma_f32 v9, v143, v219, v9
	v_fma_f32 v6, v143, v223, v6
	v_fma_f32 v7, v143, v227, v7
	v_fma_f32 v4, v143, v231, v4
	v_fma_f32 v5, v143, v235, v5
	ds_read_b128 v[204:207], v202 offset:336
	ds_read_b128 v[208:211], v202 offset:4432
	ds_read_b128 v[212:215], v202 offset:8528
	ds_read_b128 v[216:219], v202 offset:12624
	ds_read_b128 v[220:223], v202 offset:16720
	ds_read_b128 v[224:227], v202 offset:20816
	ds_read_b128 v[228:231], v202 offset:24912
	ds_read_b128 v[232:235], v202 offset:29008
	s_waitcnt vmcnt(44) lgkmcnt(8)
	v_fma_f32 v10, v144, v14, v10
	v_fma_f32 v11, v144, v18, v11
	v_fma_f32 v8, v144, v22, v8
	v_fma_f32 v9, v144, v26, v9
	v_fma_f32 v6, v144, v30, v6
	v_fma_f32 v7, v144, v34, v7
	v_fma_f32 v4, v144, v38, v4
	v_fma_f32 v5, v144, v42, v5
	v_fma_f32 v10, v145, v15, v10
	v_fma_f32 v11, v145, v19, v11
	v_fma_f32 v8, v145, v23, v8
	v_fma_f32 v9, v145, v27, v9
	v_fma_f32 v6, v145, v31, v6
	v_fma_f32 v7, v145, v35, v7
	v_fma_f32 v4, v145, v39, v4
	v_fma_f32 v5, v145, v43, v5
	v_fma_f32 v10, v146, v16, v10
	v_fma_f32 v11, v146, v20, v11
	v_fma_f32 v8, v146, v24, v8
	v_fma_f32 v9, v146, v28, v9
	v_fma_f32 v6, v146, v32, v6
	v_fma_f32 v7, v146, v36, v7
	v_fma_f32 v4, v146, v40, v4
	v_fma_f32 v5, v146, v44, v5
	v_fma_f32 v10, v147, v17, v10
	v_fma_f32 v11, v147, v21, v11
	v_fma_f32 v8, v147, v25, v8
	v_fma_f32 v9, v147, v29, v9
	v_fma_f32 v6, v147, v33, v6
	v_fma_f32 v7, v147, v37, v7
	v_fma_f32 v4, v147, v41, v4
	v_fma_f32 v5, v147, v45, v5
	ds_read_b128 v[14:17], v202 offset:352
	ds_read_b128 v[18:21], v202 offset:4448
	ds_read_b128 v[22:25], v202 offset:8544
	ds_read_b128 v[26:29], v202 offset:12640
	ds_read_b128 v[30:33], v202 offset:16736
	ds_read_b128 v[34:37], v202 offset:20832
	ds_read_b128 v[38:41], v202 offset:24928
	ds_read_b128 v[42:45], v202 offset:29024
	s_waitcnt vmcnt(40) lgkmcnt(8)
	v_fma_f32 v10, v148, v204, v10
	v_fma_f32 v11, v148, v208, v11
	v_fma_f32 v8, v148, v212, v8
	v_fma_f32 v9, v148, v216, v9
	v_fma_f32 v6, v148, v220, v6
	v_fma_f32 v7, v148, v224, v7
	v_fma_f32 v4, v148, v228, v4
	v_fma_f32 v5, v148, v232, v5
	v_fma_f32 v10, v149, v205, v10
	v_fma_f32 v11, v149, v209, v11
	v_fma_f32 v8, v149, v213, v8
	v_fma_f32 v9, v149, v217, v9
	v_fma_f32 v6, v149, v221, v6
	v_fma_f32 v7, v149, v225, v7
	v_fma_f32 v4, v149, v229, v4
	v_fma_f32 v5, v149, v233, v5
	v_fma_f32 v10, v150, v206, v10
	v_fma_f32 v11, v150, v210, v11
	v_fma_f32 v8, v150, v214, v8
	v_fma_f32 v9, v150, v218, v9
	v_fma_f32 v6, v150, v222, v6
	v_fma_f32 v7, v150, v226, v7
	v_fma_f32 v4, v150, v230, v4
	v_fma_f32 v5, v150, v234, v5
	v_fma_f32 v10, v151, v207, v10
	v_fma_f32 v11, v151, v211, v11
	v_fma_f32 v8, v151, v215, v8
	v_fma_f32 v9, v151, v219, v9
	v_fma_f32 v6, v151, v223, v6
	v_fma_f32 v7, v151, v227, v7
	v_fma_f32 v4, v151, v231, v4
	v_fma_f32 v5, v151, v235, v5
	ds_read_b128 v[204:207], v202 offset:368
	ds_read_b128 v[208:211], v202 offset:4464
	ds_read_b128 v[212:215], v202 offset:8560
	ds_read_b128 v[216:219], v202 offset:12656
	ds_read_b128 v[220:223], v202 offset:16752
	ds_read_b128 v[224:227], v202 offset:20848
	ds_read_b128 v[228:231], v202 offset:24944
	ds_read_b128 v[232:235], v202 offset:29040
	s_waitcnt vmcnt(36) lgkmcnt(8)
	v_fma_f32 v10, v152, v14, v10
	v_fma_f32 v11, v152, v18, v11
	v_fma_f32 v8, v152, v22, v8
	v_fma_f32 v9, v152, v26, v9
	v_fma_f32 v6, v152, v30, v6
	v_fma_f32 v7, v152, v34, v7
	v_fma_f32 v4, v152, v38, v4
	v_fma_f32 v5, v152, v42, v5
	v_fma_f32 v10, v153, v15, v10
	v_fma_f32 v11, v153, v19, v11
	v_fma_f32 v8, v153, v23, v8
	v_fma_f32 v9, v153, v27, v9
	v_fma_f32 v6, v153, v31, v6
	v_fma_f32 v7, v153, v35, v7
	v_fma_f32 v4, v153, v39, v4
	v_fma_f32 v5, v153, v43, v5
	v_fma_f32 v10, v154, v16, v10
	v_fma_f32 v11, v154, v20, v11
	v_fma_f32 v8, v154, v24, v8
	v_fma_f32 v9, v154, v28, v9
	v_fma_f32 v6, v154, v32, v6
	v_fma_f32 v7, v154, v36, v7
	v_fma_f32 v4, v154, v40, v4
	v_fma_f32 v5, v154, v44, v5
	v_fma_f32 v10, v155, v17, v10
	v_fma_f32 v11, v155, v21, v11
	v_fma_f32 v8, v155, v25, v8
	v_fma_f32 v9, v155, v29, v9
	v_fma_f32 v6, v155, v33, v6
	v_fma_f32 v7, v155, v37, v7
	v_fma_f32 v4, v155, v41, v4
	v_fma_f32 v5, v155, v45, v5
	ds_read_b128 v[14:17], v202 offset:384
	ds_read_b128 v[18:21], v202 offset:4480
	ds_read_b128 v[22:25], v202 offset:8576
	ds_read_b128 v[26:29], v202 offset:12672
	ds_read_b128 v[30:33], v202 offset:16768
	ds_read_b128 v[34:37], v202 offset:20864
	ds_read_b128 v[38:41], v202 offset:24960
	ds_read_b128 v[42:45], v202 offset:29056
	s_waitcnt vmcnt(32) lgkmcnt(8)
	v_fma_f32 v10, v156, v204, v10
	v_fma_f32 v11, v156, v208, v11
	v_fma_f32 v8, v156, v212, v8
	v_fma_f32 v9, v156, v216, v9
	v_fma_f32 v6, v156, v220, v6
	v_fma_f32 v7, v156, v224, v7
	v_fma_f32 v4, v156, v228, v4
	v_fma_f32 v5, v156, v232, v5
	v_fma_f32 v10, v157, v205, v10
	v_fma_f32 v11, v157, v209, v11
	v_fma_f32 v8, v157, v213, v8
	v_fma_f32 v9, v157, v217, v9
	v_fma_f32 v6, v157, v221, v6
	v_fma_f32 v7, v157, v225, v7
	v_fma_f32 v4, v157, v229, v4
	v_fma_f32 v5, v157, v233, v5
	v_fma_f32 v10, v158, v206, v10
	v_fma_f32 v11, v158, v210, v11
	v_fma_f32 v8, v158, v214, v8
	v_fma_f32 v9, v158, v218, v9
	v_fma_f32 v6, v158, v222, v6
	v_fma_f32 v7, v158, v226, v7
	v_fma_f32 v4, v158, v230, v4
	v_fma_f32 v5, v158, v234, v5
	v_fma_f32 v10, v159, v207, v10
	v_fma_f32 v11, v159, v211, v11
	v_fma_f32 v8, v159, v215, v8
	v_fma_f32 v9, v159, v219, v9
	v_fma_f32 v6, v159, v223, v6
	v_fma_f32 v7, v159, v227, v7
	v_fma_f32 v4, v159, v231, v4
	v_fma_f32 v5, v159, v235, v5
	ds_read_b128 v[204:207], v202 offset:400
	ds_read_b128 v[208:211], v202 offset:4496
	ds_read_b128 v[212:215], v202 offset:8592
	ds_read_b128 v[216:219], v202 offset:12688
	ds_read_b128 v[220:223], v202 offset:16784
	ds_read_b128 v[224:227], v202 offset:20880
	ds_read_b128 v[228:231], v202 offset:24976
	ds_read_b128 v[232:235], v202 offset:29072
	s_waitcnt vmcnt(28) lgkmcnt(8)
	v_fma_f32 v10, v160, v14, v10
	v_fma_f32 v11, v160, v18, v11
	v_fma_f32 v8, v160, v22, v8
	v_fma_f32 v9, v160, v26, v9
	v_fma_f32 v6, v160, v30, v6
	v_fma_f32 v7, v160, v34, v7
	v_fma_f32 v4, v160, v38, v4
	v_fma_f32 v5, v160, v42, v5
	v_fma_f32 v10, v161, v15, v10
	v_fma_f32 v11, v161, v19, v11
	v_fma_f32 v8, v161, v23, v8
	v_fma_f32 v9, v161, v27, v9
	v_fma_f32 v6, v161, v31, v6
	v_fma_f32 v7, v161, v35, v7
	v_fma_f32 v4, v161, v39, v4
	v_fma_f32 v5, v161, v43, v5
	v_fma_f32 v10, v162, v16, v10
	v_fma_f32 v11, v162, v20, v11
	v_fma_f32 v8, v162, v24, v8
	v_fma_f32 v9, v162, v28, v9
	v_fma_f32 v6, v162, v32, v6
	v_fma_f32 v7, v162, v36, v7
	v_fma_f32 v4, v162, v40, v4
	v_fma_f32 v5, v162, v44, v5
	v_fma_f32 v10, v163, v17, v10
	v_fma_f32 v11, v163, v21, v11
	v_fma_f32 v8, v163, v25, v8
	v_fma_f32 v9, v163, v29, v9
	v_fma_f32 v6, v163, v33, v6
	v_fma_f32 v7, v163, v37, v7
	v_fma_f32 v4, v163, v41, v4
	v_fma_f32 v5, v163, v45, v5
	ds_read_b128 v[14:17], v202 offset:416
	ds_read_b128 v[18:21], v202 offset:4512
	ds_read_b128 v[22:25], v202 offset:8608
	ds_read_b128 v[26:29], v202 offset:12704
	ds_read_b128 v[30:33], v202 offset:16800
	ds_read_b128 v[34:37], v202 offset:20896
	ds_read_b128 v[38:41], v202 offset:24992
	ds_read_b128 v[42:45], v202 offset:29088
	s_waitcnt vmcnt(24) lgkmcnt(8)
	v_fma_f32 v10, v164, v204, v10
	v_fma_f32 v11, v164, v208, v11
	v_fma_f32 v8, v164, v212, v8
	v_fma_f32 v9, v164, v216, v9
	v_fma_f32 v6, v164, v220, v6
	v_fma_f32 v7, v164, v224, v7
	v_fma_f32 v4, v164, v228, v4
	v_fma_f32 v5, v164, v232, v5
	v_fma_f32 v10, v165, v205, v10
	v_fma_f32 v11, v165, v209, v11
	v_fma_f32 v8, v165, v213, v8
	v_fma_f32 v9, v165, v217, v9
	v_fma_f32 v6, v165, v221, v6
	v_fma_f32 v7, v165, v225, v7
	v_fma_f32 v4, v165, v229, v4
	v_fma_f32 v5, v165, v233, v5
	v_fma_f32 v10, v166, v206, v10
	v_fma_f32 v11, v166, v210, v11
	v_fma_f32 v8, v166, v214, v8
	v_fma_f32 v9, v166, v218, v9
	v_fma_f32 v6, v166, v222, v6
	v_fma_f32 v7, v166, v226, v7
	v_fma_f32 v4, v166, v230, v4
	v_fma_f32 v5, v166, v234, v5
	v_fma_f32 v10, v167, v207, v10
	v_fma_f32 v11, v167, v211, v11
	v_fma_f32 v8, v167, v215, v8
	v_fma_f32 v9, v167, v219, v9
	v_fma_f32 v6, v167, v223, v6
	v_fma_f32 v7, v167, v227, v7
	v_fma_f32 v4, v167, v231, v4
	v_fma_f32 v5, v167, v235, v5
	ds_read_b128 v[204:207], v202 offset:432
	ds_read_b128 v[208:211], v202 offset:4528
	ds_read_b128 v[212:215], v202 offset:8624
	ds_read_b128 v[216:219], v202 offset:12720
	ds_read_b128 v[220:223], v202 offset:16816
	ds_read_b128 v[224:227], v202 offset:20912
	ds_read_b128 v[228:231], v202 offset:25008
	ds_read_b128 v[232:235], v202 offset:29104
	s_waitcnt vmcnt(20) lgkmcnt(8)
	v_fma_f32 v10, v168, v14, v10
	v_fma_f32 v11, v168, v18, v11
	v_fma_f32 v8, v168, v22, v8
	v_fma_f32 v9, v168, v26, v9
	v_fma_f32 v6, v168, v30, v6
	v_fma_f32 v7, v168, v34, v7
	v_fma_f32 v4, v168, v38, v4
	v_fma_f32 v5, v168, v42, v5
	v_fma_f32 v10, v169, v15, v10
	v_fma_f32 v11, v169, v19, v11
	v_fma_f32 v8, v169, v23, v8
	v_fma_f32 v9, v169, v27, v9
	v_fma_f32 v6, v169, v31, v6
	v_fma_f32 v7, v169, v35, v7
	v_fma_f32 v4, v169, v39, v4
	v_fma_f32 v5, v169, v43, v5
	v_fma_f32 v10, v170, v16, v10
	v_fma_f32 v11, v170, v20, v11
	v_fma_f32 v8, v170, v24, v8
	v_fma_f32 v9, v170, v28, v9
	v_fma_f32 v6, v170, v32, v6
	v_fma_f32 v7, v170, v36, v7
	v_fma_f32 v4, v170, v40, v4
	v_fma_f32 v5, v170, v44, v5
	v_fma_f32 v10, v171, v17, v10
	v_fma_f32 v11, v171, v21, v11
	v_fma_f32 v8, v171, v25, v8
	v_fma_f32 v9, v171, v29, v9
	v_fma_f32 v6, v171, v33, v6
	v_fma_f32 v7, v171, v37, v7
	v_fma_f32 v4, v171, v41, v4
	v_fma_f32 v5, v171, v45, v5
	ds_read_b128 v[14:17], v202 offset:448
	ds_read_b128 v[18:21], v202 offset:4544
	ds_read_b128 v[22:25], v202 offset:8640
	ds_read_b128 v[26:29], v202 offset:12736
	ds_read_b128 v[30:33], v202 offset:16832
	ds_read_b128 v[34:37], v202 offset:20928
	ds_read_b128 v[38:41], v202 offset:25024
	ds_read_b128 v[42:45], v202 offset:29120
	s_waitcnt vmcnt(16) lgkmcnt(8)
	v_fma_f32 v10, v172, v204, v10
	v_fma_f32 v11, v172, v208, v11
	v_fma_f32 v8, v172, v212, v8
	v_fma_f32 v9, v172, v216, v9
	v_fma_f32 v6, v172, v220, v6
	v_fma_f32 v7, v172, v224, v7
	v_fma_f32 v4, v172, v228, v4
	v_fma_f32 v5, v172, v232, v5
	v_fma_f32 v10, v173, v205, v10
	v_fma_f32 v11, v173, v209, v11
	v_fma_f32 v8, v173, v213, v8
	v_fma_f32 v9, v173, v217, v9
	v_fma_f32 v6, v173, v221, v6
	v_fma_f32 v7, v173, v225, v7
	v_fma_f32 v4, v173, v229, v4
	v_fma_f32 v5, v173, v233, v5
	v_fma_f32 v10, v174, v206, v10
	v_fma_f32 v11, v174, v210, v11
	v_fma_f32 v8, v174, v214, v8
	v_fma_f32 v9, v174, v218, v9
	v_fma_f32 v6, v174, v222, v6
	v_fma_f32 v7, v174, v226, v7
	v_fma_f32 v4, v174, v230, v4
	v_fma_f32 v5, v174, v234, v5
	v_fma_f32 v10, v175, v207, v10
	v_fma_f32 v11, v175, v211, v11
	v_fma_f32 v8, v175, v215, v8
	v_fma_f32 v9, v175, v219, v9
	v_fma_f32 v6, v175, v223, v6
	v_fma_f32 v7, v175, v227, v7
	v_fma_f32 v4, v175, v231, v4
	v_fma_f32 v5, v175, v235, v5
	ds_read_b128 v[204:207], v202 offset:464
	ds_read_b128 v[208:211], v202 offset:4560
	ds_read_b128 v[212:215], v202 offset:8656
	ds_read_b128 v[216:219], v202 offset:12752
	ds_read_b128 v[220:223], v202 offset:16848
	ds_read_b128 v[224:227], v202 offset:20944
	ds_read_b128 v[228:231], v202 offset:25040
	ds_read_b128 v[232:235], v202 offset:29136
	s_waitcnt vmcnt(12) lgkmcnt(8)
	v_fma_f32 v10, v176, v14, v10
	v_fma_f32 v11, v176, v18, v11
	v_fma_f32 v8, v176, v22, v8
	v_fma_f32 v9, v176, v26, v9
	v_fma_f32 v6, v176, v30, v6
	v_fma_f32 v7, v176, v34, v7
	v_fma_f32 v4, v176, v38, v4
	v_fma_f32 v5, v176, v42, v5
	v_fma_f32 v10, v177, v15, v10
	v_fma_f32 v11, v177, v19, v11
	v_fma_f32 v8, v177, v23, v8
	v_fma_f32 v9, v177, v27, v9
	v_fma_f32 v6, v177, v31, v6
	v_fma_f32 v7, v177, v35, v7
	v_fma_f32 v4, v177, v39, v4
	v_fma_f32 v5, v177, v43, v5
	v_fma_f32 v10, v178, v16, v10
	v_fma_f32 v11, v178, v20, v11
	v_fma_f32 v8, v178, v24, v8
	v_fma_f32 v9, v178, v28, v9
	v_fma_f32 v6, v178, v32, v6
	v_fma_f32 v7, v178, v36, v7
	v_fma_f32 v4, v178, v40, v4
	v_fma_f32 v5, v178, v44, v5
	v_fma_f32 v10, v180, v17, v10
	v_fma_f32 v11, v180, v21, v11
	v_fma_f32 v8, v180, v25, v8
	v_fma_f32 v9, v180, v29, v9
	v_fma_f32 v6, v180, v33, v6
	v_fma_f32 v7, v180, v37, v7
	v_fma_f32 v4, v180, v41, v4
	v_fma_f32 v5, v180, v45, v5
	ds_read_b128 v[14:17], v202 offset:480
	ds_read_b128 v[18:21], v202 offset:4576
	ds_read_b128 v[22:25], v202 offset:8672
	ds_read_b128 v[26:29], v202 offset:12768
	ds_read_b128 v[30:33], v202 offset:16864
	ds_read_b128 v[34:37], v202 offset:20960
	ds_read_b128 v[38:41], v202 offset:25056
	ds_read_b128 v[42:45], v202 offset:29152
	s_waitcnt vmcnt(8) lgkmcnt(8)
	v_fma_f32 v10, v181, v204, v10
	v_fma_f32 v11, v181, v208, v11
	v_fma_f32 v8, v181, v212, v8
	v_fma_f32 v9, v181, v216, v9
	v_fma_f32 v6, v181, v220, v6
	v_fma_f32 v7, v181, v224, v7
	v_fma_f32 v4, v181, v228, v4
	v_fma_f32 v5, v181, v232, v5
	v_fma_f32 v10, v182, v205, v10
	v_fma_f32 v11, v182, v209, v11
	v_fma_f32 v8, v182, v213, v8
	v_fma_f32 v9, v182, v217, v9
	v_fma_f32 v6, v182, v221, v6
	v_fma_f32 v7, v182, v225, v7
	v_fma_f32 v4, v182, v229, v4
	v_fma_f32 v5, v182, v233, v5
	v_fma_f32 v10, v183, v206, v10
	v_fma_f32 v11, v183, v210, v11
	v_fma_f32 v8, v183, v214, v8
	v_fma_f32 v9, v183, v218, v9
	v_fma_f32 v6, v183, v222, v6
	v_fma_f32 v7, v183, v226, v7
	v_fma_f32 v4, v183, v230, v4
	v_fma_f32 v5, v183, v234, v5
	v_fma_f32 v10, v184, v207, v10
	v_fma_f32 v11, v184, v211, v11
	v_fma_f32 v8, v184, v215, v8
	v_fma_f32 v9, v184, v219, v9
	v_fma_f32 v6, v184, v223, v6
	v_fma_f32 v7, v184, v227, v7
	v_fma_f32 v4, v184, v231, v4
	v_fma_f32 v5, v184, v235, v5
	ds_read_b128 v[204:207], v202 offset:496
	ds_read_b128 v[208:211], v202 offset:4592
	ds_read_b128 v[212:215], v202 offset:8688
	ds_read_b128 v[216:219], v202 offset:12784
	ds_read_b128 v[220:223], v202 offset:16880
	ds_read_b128 v[224:227], v202 offset:20976
	ds_read_b128 v[228:231], v202 offset:25072
	ds_read_b128 v[232:235], v202 offset:29168
	s_waitcnt vmcnt(4) lgkmcnt(8)
	v_fma_f32 v10, v185, v14, v10
	v_fma_f32 v11, v185, v18, v11
	v_fma_f32 v8, v185, v22, v8
	v_fma_f32 v9, v185, v26, v9
	v_fma_f32 v6, v185, v30, v6
	v_fma_f32 v7, v185, v34, v7
	v_fma_f32 v4, v185, v38, v4
	v_fma_f32 v5, v185, v42, v5
	v_fma_f32 v10, v186, v15, v10
	v_fma_f32 v11, v186, v19, v11
	v_fma_f32 v8, v186, v23, v8
	v_fma_f32 v9, v186, v27, v9
	v_fma_f32 v6, v186, v31, v6
	v_fma_f32 v7, v186, v35, v7
	v_fma_f32 v4, v186, v39, v4
	v_fma_f32 v5, v186, v43, v5
	v_fma_f32 v10, v187, v16, v10
	v_fma_f32 v11, v187, v20, v11
	v_fma_f32 v8, v187, v24, v8
	v_fma_f32 v9, v187, v28, v9
	v_fma_f32 v6, v187, v32, v6
	v_fma_f32 v7, v187, v36, v7
	v_fma_f32 v4, v187, v40, v4
	v_fma_f32 v5, v187, v44, v5
	v_fma_f32 v10, v188, v17, v10
	v_fma_f32 v11, v188, v21, v11
	v_fma_f32 v8, v188, v25, v8
	v_fma_f32 v9, v188, v29, v9
	v_fma_f32 v6, v188, v33, v6
	v_fma_f32 v7, v188, v37, v7
	v_fma_f32 v4, v188, v41, v4
	v_fma_f32 v5, v188, v45, v5
	s_waitcnt vmcnt(0) lgkmcnt(0)
	v_fma_f32 v10, v189, v204, v10
	v_fma_f32 v11, v189, v208, v11
	v_fma_f32 v8, v189, v212, v8
	v_fma_f32 v9, v189, v216, v9
	v_fma_f32 v6, v189, v220, v6
	v_fma_f32 v7, v189, v224, v7
	v_fma_f32 v4, v189, v228, v4
	v_fma_f32 v5, v189, v232, v5
	v_fma_f32 v10, v190, v205, v10
	v_fma_f32 v11, v190, v209, v11
	v_fma_f32 v8, v190, v213, v8
	v_fma_f32 v9, v190, v217, v9
	v_fma_f32 v6, v190, v221, v6
	v_fma_f32 v7, v190, v225, v7
	v_fma_f32 v4, v190, v229, v4
	v_fma_f32 v5, v190, v233, v5
	v_fma_f32 v10, v191, v206, v10
	v_fma_f32 v11, v191, v210, v11
	v_fma_f32 v8, v191, v214, v8
	v_fma_f32 v9, v191, v218, v9
	v_fma_f32 v6, v191, v222, v6
	v_fma_f32 v7, v191, v226, v7
	v_fma_f32 v4, v191, v230, v4
	v_fma_f32 v5, v191, v234, v5
	v_fma_f32 v10, v192, v207, v10
	v_fma_f32 v11, v192, v211, v11
	v_fma_f32 v8, v192, v215, v8
	v_fma_f32 v9, v192, v219, v9
	v_fma_f32 v6, v192, v223, v6
	v_fma_f32 v7, v192, v227, v7
	v_fma_f32 v4, v192, v231, v4
	v_fma_f32 v5, v192, v235, v5
	s_cmp_eq_u32 s9, 0
	v_mov_b32_e32 v12, 0
	s_cbranch_scc0 .LBB0_19
	s_mul_i32 s0, s8, 0x2400
	v_add_u32_e32 v12, s0, v2
	v_readlane_b32 s36, v249, 0
	v_ashrrev_i32_e32 v13, 31, v12
	v_readlane_b32 s42, v249, 6
	v_readlane_b32 s43, v249, 7
	v_readlane_b32 s37, v249, 1
	v_readlane_b32 s38, v249, 2
	v_lshl_add_u64 v[12:13], v[12:13], 2, s[42:43]
	global_load_dword v12, v[12:13], off
	v_readlane_b32 s39, v249, 3
	v_readlane_b32 s40, v249, 4
	v_readlane_b32 s41, v249, 5
	s_branch .LBB0_19
